# v_full8 + weights phase: the eight per-row gain loads of a tile issued together (one wait instead of eight round trips)
# baseline (speedup 1.0000x reference)
.LBB0_88:
	s_mul_i32 s27, s27, s26
	s_sub_i32 s22, s28, s27
	s_lshl_b32 s22, s22, 6
	v_ashrrev_i32_e32 v41, 6, v39
	v_add_u32_e32 v34, s22, v41
	v_ashrrev_i32_e32 v3, 31, v2
	v_ashrrev_i32_e32 v35, 31, v34
	v_lshl_add_u64 v[2:3], v[2:3], 2, s[12:13]
	v_mul_lo_u32 v6, s24, v35
	v_mul_lo_u32 v7, s25, v34
	v_mad_u64_u32 v[4:5], s[12:13], s24, v34, 0
	v_add3_u32 v5, v5, v6, v7
	v_add_u32_e32 v6, 8, v34
	v_ashrrev_i32_e32 v7, 31, v6
	v_mul_lo_u32 v8, s24, v7
	v_mul_lo_u32 v9, s25, v6
	v_mad_u64_u32 v[6:7], s[12:13], s24, v6, 0
	v_lshl_add_u64 v[4:5], v[4:5], 2, v[2:3]
	v_add3_u32 v7, v7, v8, v9
	v_lshl_add_u64 v[6:7], v[6:7], 2, v[2:3]
	global_load_dwordx4 v[30:33], v[4:5], off
	global_load_dwordx4 v[22:25], v[6:7], off
	v_add_u32_e32 v4, 16, v34
	v_ashrrev_i32_e32 v5, 31, v4
	v_mul_lo_u32 v6, s24, v5
	v_mul_lo_u32 v7, s25, v4
	v_mad_u64_u32 v[4:5], s[12:13], s24, v4, 0
	v_add3_u32 v5, v5, v6, v7
	v_add_u32_e32 v6, 24, v34
	v_ashrrev_i32_e32 v7, 31, v6
	v_mul_lo_u32 v8, s24, v7
	v_mul_lo_u32 v9, s25, v6
	v_mad_u64_u32 v[6:7], s[12:13], s24, v6, 0
	v_lshl_add_u64 v[4:5], v[4:5], 2, v[2:3]
	v_add3_u32 v7, v7, v8, v9
	v_lshl_add_u64 v[6:7], v[6:7], 2, v[2:3]
	global_load_dwordx4 v[26:29], v[4:5], off
	global_load_dwordx4 v[14:17], v[6:7], off
	v_add_u32_e32 v4, 32, v34
	v_ashrrev_i32_e32 v5, 31, v4
	v_mul_lo_u32 v6, s24, v5
	v_mul_lo_u32 v7, s25, v4
	v_mad_u64_u32 v[4:5], s[12:13], s24, v4, 0
	v_add3_u32 v5, v5, v6, v7
	v_add_u32_e32 v6, 40, v34
	v_ashrrev_i32_e32 v7, 31, v6
	v_mul_lo_u32 v8, s24, v7
	v_mul_lo_u32 v9, s25, v6
	v_mad_u64_u32 v[6:7], s[12:13], s24, v6, 0
	v_add3_u32 v7, v7, v8, v9
	v_lshl_add_u64 v[4:5], v[4:5], 2, v[2:3]
	v_lshl_add_u64 v[6:7], v[6:7], 2, v[2:3]
	global_load_dwordx4 v[18:21], v[4:5], off
	s_nop 0
	global_load_dwordx4 v[6:9], v[6:7], off
	v_add_u32_e32 v4, 48, v34
	v_ashrrev_i32_e32 v5, 31, v4
	v_mul_lo_u32 v10, s24, v5
	v_mul_lo_u32 v11, s25, v4
	v_mad_u64_u32 v[4:5], s[12:13], s24, v4, 0
	v_add3_u32 v5, v5, v10, v11
	v_add_u32_e32 v10, 56, v34
	v_ashrrev_i32_e32 v11, 31, v10
	v_mul_lo_u32 v12, s24, v11
	v_mul_lo_u32 v13, s25, v10
	v_mad_u64_u32 v[10:11], s[12:13], s24, v10, 0
	v_add3_u32 v11, v11, v12, v13
	v_lshl_add_u64 v[4:5], v[4:5], 2, v[2:3]
	v_lshl_add_u64 v[2:3], v[10:11], 2, v[2:3]
	global_load_dwordx4 v[10:13], v[4:5], off
	s_nop 0
	global_load_dwordx4 v[2:5], v[2:3], off
	s_cmp_lg_u64 s[2:3], 0
	v_mov_b32_e32 v36, 1.0
	s_cselect_b64 s[12:13], -1, 0
	s_cmp_eq_u64 s[2:3], 0
	v_lshl_add_u64 v[34:35], v[34:35], 2, s[2:3]
	s_cbranch_scc1 .Lmy_w_nogain
	global_load_dword v192, v[34:35], off
	global_load_dword v194, v[34:35], off offset:32
	global_load_dword v196, v[34:35], off offset:64
	global_load_dword v198, v[34:35], off offset:96
	global_load_dword v200, v[34:35], off offset:128
	global_load_dword v202, v[34:35], off offset:160
	global_load_dword v204, v[34:35], off offset:192
	global_load_dword v206, v[34:35], off offset:224
.Lmy_w_nogain:
	v_mov_b32_e32 v38, 1.0
	s_cbranch_scc1 .LBB0_90
	s_waitcnt vmcnt(0)
	v_mov_b32_e32 v38, v192
.LBB0_90:
	v_lshl_add_u32 v40, v40, 2, 0
	v_mul_lo_u32 v41, v41, s14
	v_add_u32_e32 v40, v40, v41
	s_waitcnt vmcnt(0)
	v_pk_mul_f32 v[30:31], v[30:31], v[38:39] op_sel_hi:[1,0]
	ds_write2_b32 v40, v30, v31 offset1:1
	v_pk_mul_f32 v[30:31], v[32:33], v[38:39] op_sel_hi:[1,0]
	v_cndmask_b32_e64 v32, 0, 1, s[12:13]
	v_cmp_ne_u32_e64 s[2:3], 1, v32
	s_andn2_b64 vcc, exec, s[12:13]
	ds_write2_b32 v40, v30, v31 offset0:2 offset1:3
	s_cbranch_vccnz .LBB0_92
	v_mov_b32_e32 v36, v194
.LBB0_92:
	v_add_u32_e32 v30, 0x2020, v40
	s_waitcnt vmcnt(0)
	v_pk_mul_f32 v[22:23], v[22:23], v[36:37] op_sel_hi:[1,0]
	ds_write2_b32 v30, v22, v23 offset1:1
	v_pk_mul_f32 v[22:23], v[24:25], v[36:37] op_sel_hi:[1,0]
	v_add_u32_e32 v24, 0x2028, v40
	ds_write2_b32 v24, v22, v23 offset1:1
	v_mov_b32_e32 v22, 1.0
	s_and_b64 vcc, exec, s[2:3]
	v_mov_b32_e32 v24, 1.0
	s_cbranch_vccnz .LBB0_94
	v_mov_b32_e32 v24, v196
.LBB0_94:
	s_waitcnt vmcnt(0)
	v_pk_mul_f32 v[26:27], v[26:27], v[24:25] op_sel_hi:[1,0]
	v_add_u32_e32 v23, 0x4040, v40
	ds_write2_b32 v23, v26, v27 offset1:1
	v_pk_mul_f32 v[24:25], v[28:29], v[24:25] op_sel_hi:[1,0]
	v_add_u32_e32 v23, 0x4048, v40
	s_and_b64 vcc, exec, s[2:3]
	ds_write2_b32 v23, v24, v25 offset1:1
	s_cbranch_vccnz .LBB0_96
	v_mov_b32_e32 v22, v198
.LBB0_96:
	s_waitcnt vmcnt(0)
	v_pk_mul_f32 v[14:15], v[14:15], v[22:23] op_sel_hi:[1,0]
	v_add_u32_e32 v23, 0x6060, v40
	ds_write2_b32 v23, v14, v15 offset1:1
	v_pk_mul_f32 v[14:15], v[16:17], v[22:23] op_sel_hi:[1,0]
	v_add_u32_e32 v16, 0x6068, v40
	ds_write2_b32 v16, v14, v15 offset1:1
	v_mov_b32_e32 v14, 1.0
	s_and_b64 vcc, exec, s[2:3]
	v_mov_b32_e32 v16, 1.0
	s_cbranch_vccnz .LBB0_98
	v_mov_b32_e32 v16, v200
.LBB0_98:
	s_waitcnt vmcnt(0)
	v_pk_mul_f32 v[18:19], v[18:19], v[16:17] op_sel_hi:[1,0]
	v_add_u32_e32 v15, 0x8080, v40
	ds_write2_b32 v15, v18, v19 offset1:1
	v_pk_mul_f32 v[16:17], v[20:21], v[16:17] op_sel_hi:[1,0]
	v_add_u32_e32 v15, 0x8088, v40
	s_and_b64 vcc, exec, s[2:3]
	ds_write2_b32 v15, v16, v17 offset1:1
	s_cbranch_vccnz .LBB0_100
	v_mov_b32_e32 v14, v202
.LBB0_100:
	s_waitcnt vmcnt(0)
	v_pk_mul_f32 v[6:7], v[6:7], v[14:15] op_sel_hi:[1,0]
	v_add_u32_e32 v15, 0xa0a0, v40
	ds_write2_b32 v15, v6, v7 offset1:1
	v_pk_mul_f32 v[6:7], v[8:9], v[14:15] op_sel_hi:[1,0]
	v_add_u32_e32 v8, 0xa0a8, v40
	ds_write2_b32 v8, v6, v7 offset1:1
	v_mov_b32_e32 v6, 1.0
	s_and_b64 vcc, exec, s[2:3]
	v_mov_b32_e32 v8, 1.0
	s_cbranch_vccnz .LBB0_102
	v_mov_b32_e32 v8, v204
.LBB0_102:
	s_waitcnt vmcnt(0)
	v_pk_mul_f32 v[10:11], v[10:11], v[8:9] op_sel_hi:[1,0]
	v_add_u32_e32 v7, 0xc0c0, v40
	ds_write2_b32 v7, v10, v11 offset1:1
	v_pk_mul_f32 v[8:9], v[12:13], v[8:9] op_sel_hi:[1,0]
	v_add_u32_e32 v7, 0xc0c8, v40
	s_and_b64 vcc, exec, s[2:3]
	ds_write2_b32 v7, v8, v9 offset1:1
	s_cbranch_vccnz .LBB0_57
	v_mov_b32_e32 v6, v206
	s_branch .LBB0_57
